# grid barrier: the XCD leader that wrote back L2 adds to one top counter that every workgroup polls (top ticket/generation and per-XCD generation relays removed)
# speedup vs baseline: 1.0361x; 1.0050x over previous
; #define LAS __attribute__((address_space(3)))
; __device__ __forceinline__ unsigned xb_add(unsigned* p, unsigned v) { return __hip_atomic_fetch_add(p, v, __ATOMIC_RELAXED, __HIP_MEMORY_SCOPE_AGENT); }
; __device__ __forceinline__ unsigned xb_xcc_id() { return (unsigned)__builtin_amdgcn_s_getreg((3 << 11) | 20) & 0xFu; }
; __device__ __forceinline__ XcdBarrier xcd_barrier_post(unsigned* bar, volatile LAS unsigned* st) {
;     XcdBarrier b; b.bar = bar; b.x = xb_xcc_id(); b.st = st;
;     if (threadIdx.x == 0) (void)xb_add(&bar[XB_XCNT(b.x)], 1u);
;     return b;
; template <bool COOP>
; __global__ void __launch_bounds__(NTHREADS, 2) mega(Params p0) {
;     extern __shared__ __attribute__((aligned(16))) unsigned char lds[];
;     const int G = gridDim.x;
;     XcdBarrier xbar; xbar.bar = nullptr; xbar.x = 0; xbar.st = nullptr;
;     if (COOP) {
;         volatile LAS unsigned* st = (volatile LAS unsigned*)((LAS unsigned char*)lds + (LDS_BYTES - 16));
;         if (threadIdx.x < 4) st[threadIdx.x] = 0u;
;         __syncthreads();
;         xbar = xcd_barrier_post((unsigned*)(p0.ws + WS_BAR), st);
;     }
_Z4megaILb1EEv6Params:
	s_load_dwordx4 s[80:83], s[0:1], 0xd8
	s_load_dword s89, s[0:1], 0xe8
	s_mov_b32 s86, s2
	s_mov_b32 s32, 0
	s_add_u32 s2, s0, 0xe8
	s_addc_u32 s3, s1, 0
	v_and_b32_e32 v238, 0x3ff, v0
	v_writelane_b32 v251, s2, 0
	v_cmp_gt_u32_e32 vcc, 4, v238
	s_nop 0
	v_writelane_b32 v251, s3, 1
	s_and_saveexec_b64 s[2:3], vcc
	v_lshl_add_u32 v1, v238, 2, 0
	v_add_u32_e32 v1, 0x23ff0, v1
	v_mov_b32_e32 v2, 0
	ds_write_b32 v1, v2
	s_or_b64 exec, exec, s[2:3]
	s_waitcnt lgkmcnt(0)
	s_barrier
	s_add_u32 s2, s80, 0x347a0000
	s_getreg_b32 s4, hwreg(HW_REG_XCC_ID, 0, 4)
	s_addc_u32 s3, s81, 0
	s_and_b32 s8, s4, 15
	v_cmp_eq_u32_e64 s[6:7], 0, v238
	s_mov_b64 s[4:5], exec
	s_nop 0
	v_writelane_b32 v251, s6, 2
	s_nop 1
	v_writelane_b32 v251, s7, 3
	s_and_b64 s[6:7], s[4:5], s[6:7]
	s_mov_b64 exec, s[6:7]
	s_cbranch_execz .LBB0_5
	s_mov_b64 s[6:7], exec
	v_mbcnt_lo_u32_b32 v1, s6, 0
	v_mbcnt_hi_u32_b32 v1, s7, v1
	v_cmp_eq_u32_e32 vcc, 0, v1
	s_and_b64 s[10:11], exec, vcc
	s_mov_b64 exec, s[10:11]
	s_cbranch_execz .LBB0_5
	s_lshl_b32 s9, s8, 8
	s_bcnt1_i32_b64 s6, s[6:7]
	v_mov_b32_e32 v1, s9
	v_mov_b32_e32 v2, s6
	global_atomic_add v1, v2, s[2:3] offset:1024

; __device__ __forceinline__ void xcd_barrier(const XcdBarrier& b) {
;     asm volatile("s_waitcnt vmcnt(0)" ::: "memory");
;     __syncthreads();
;     if (threadIdx.x == 0) {
;         unsigned* bar = b.bar;
;         __builtin_amdgcn_s_waitcnt(0);
;         unsigned nloc = b.st[0], nx = b.st[1];
;         if (nloc == 0u) { xcd_barrier_complete(bar, b.x, nloc, nx); b.st[0] = nloc; b.st[1] = nx; }
.LBB0_551:
	v_readlane_b32 s4, v251, 11
	v_readlane_b32 s5, v251, 12
	s_mov_b64 s[0:1], -1
	s_and_b64 vcc, exec, s[4:5]
	s_cbranch_vccz .LBB0_605
	s_waitcnt vmcnt(0)
	s_waitcnt vmcnt(0) lgkmcnt(0)
	s_barrier
	s_mov_b64 s[0:1], exec
	v_readlane_b32 s4, v251, 2
	v_readlane_b32 s5, v251, 3
	s_and_b64 s[4:5], s[0:1], s[4:5]
	s_mov_b64 exec, s[4:5]
	s_cbranch_execz .LBB0_604
	s_add_i32 s32, s32, 1
	v_readlane_b32 s4, v253, 17
	s_waitcnt vmcnt(0) expcnt(0) lgkmcnt(0)
	s_nop 0
	v_mov_b32_e32 v0, s4
	ds_read_b32 v2, v0
	v_readlane_b32 s4, v253, 18
	s_waitcnt lgkmcnt(0)
	v_cmp_ne_u32_e32 vcc, 0, v2
	v_mov_b32_e32 v0, s4
	ds_read_b32 v0, v0
	s_cbranch_vccnz .LBB0_568
	v_readlane_b32 s6, v251, 0
	v_readlane_b32 s7, v251, 1
	s_load_dwordx2 s[4:5], s[6:7], 0x4
	s_mov_b32 s28, 1
	s_waitcnt lgkmcnt(0)
	s_mul_i32 s10, s4, s89
	s_mul_i32 s10, s10, s5
	s_branch .LBB0_556

; __device__ __forceinline__ unsigned xb_ld(unsigned* p)              { return __hip_atomic_load(p, __ATOMIC_RELAXED, __HIP_MEMORY_SCOPE_AGENT); }
; __device__ __forceinline__ unsigned xb_add(unsigned* p, unsigned v) { return __hip_atomic_fetch_add(p, v, __ATOMIC_RELAXED, __HIP_MEMORY_SCOPE_AGENT); }
; #define XB_SPIN(cond, bar) do { unsigned _sp = 0; while (cond) { __builtin_amdgcn_s_sleep(1); \
;     if ((++_sp & 255u) == 0u) { if (xb_ld(&(bar)[XB_TMO])) break; if (_sp > XB_SPIN_CAP) { atomicAdd(&(bar)[XB_TMO], 1u); break; } } } } while (0)
; __device__ __forceinline__ void xcd_barrier(const XcdBarrier& b) {
;     ...
;         const unsigned old = xb_add(&bar[XB_XSUB(b.x)], 1u);
;         const unsigned gen = old / nloc;
;         if (old + 1u == (gen + 1u) * nloc) {
;             __builtin_amdgcn_fence(__ATOMIC_RELEASE, "agent");
;             asm volatile("s_waitcnt vmcnt(0)" ::: "memory");
;             const unsigned og = xb_add(&bar[XB_TOP], 1u);
;             const unsigned tg = og / nx;
;             if (og + 1u == (tg + 1u) * nx) xb_add(&bar[XB_TOPGEN], 1u);
;             else XB_SPIN(xb_ld(&bar[XB_TOPGEN]) == tg, bar);
;             __builtin_amdgcn_fence(__ATOMIC_ACQUIRE, "agent");
;             xb_add(&bar[XB_XGEN(b.x)], 1u);
;             asm volatile("s_waitcnt vmcnt(0)" ::: "memory");
;         } else {
;             XB_SPIN(xb_ld(&bar[XB_XGEN(b.x)]) == gen, bar);
;             __builtin_amdgcn_fence(__ATOMIC_ACQUIRE, "agent");
;             asm volatile("s_waitcnt vmcnt(0)" ::: "memory");
;         }
.LBB0_570:
	s_or_b64 exec, exec, s[4:5]
	v_cvt_f32_u32_e32 v5, v2
	s_waitcnt vmcnt(0)
	v_readfirstlane_b32 s4, v4
	v_sub_u32_e32 v4, 0, v2
	v_rcp_iflag_f32_e32 v5, v5
	v_add_u32_e32 v6, s4, v1
	v_mul_f32_e32 v5, 0x4f7ffffe, v5
	v_cvt_u32_f32_e32 v5, v5
	v_mul_lo_u32 v1, v4, v5
	v_mul_hi_u32 v1, v5, v1
	v_add_u32_e32 v1, v5, v1
	v_mul_hi_u32 v1, v6, v1
	v_mul_lo_u32 v4, v1, v2
	v_sub_u32_e32 v4, v6, v4
	v_add_u32_e32 v5, 1, v1
	v_cmp_ge_u32_e32 vcc, v4, v2
	s_nop 1
	v_cndmask_b32_e32 v1, v1, v5, vcc
	v_sub_u32_e32 v5, v4, v2
	v_cndmask_b32_e32 v4, v4, v5, vcc
	v_add_u32_e32 v5, 1, v1
	v_cmp_ge_u32_e32 vcc, v4, v2
	v_add_u32_e32 v4, 1, v6
	s_nop 0
	v_cndmask_b32_e32 v1, v1, v5, vcc
	v_mul_lo_u32 v5, v2, v1
	v_add_u32_e32 v2, v5, v2
	v_cmp_ne_u32_e32 vcc, v4, v2
	s_waitcnt lgkmcnt(0)
	v_readfirstlane_b32 s8, v0
	v_readlane_b32 s6, v253, 63
	v_readlane_b32 s7, v254, 0
	s_mul_i32 s8, s8, s32
	s_add_u32 s6, s6, 0x347a3800
	s_addc_u32 s7, s7, 0
	s_cbranch_vccnz .Lgb_poll
	buffer_wbl2 sc1
	s_waitcnt vmcnt(0)
	v_mov_b32_e32 v1, 1
	global_atomic_add v3, v1, s[6:7]
.Lgb_poll:
	s_mov_b32 s9, 0
.Lgb_spin:
	global_load_dword v1, v3, s[6:7] sc1
	s_waitcnt vmcnt(0)
	v_readfirstlane_b32 s10, v1
	s_sub_i32 s10, s10, s8
	s_cmp_ge_i32 s10, 0
	s_cbranch_scc1 .Lgb_done
	s_sleep 1
	s_add_u32 s9, s9, 1
	s_cmp_lt_u32 s9, 0x8000
	s_cbranch_scc1 .Lgb_spin
.Lgb_done:
	buffer_inv sc1
	s_waitcnt vmcnt(0)
